# GLA: raw q/k for the decay stage read by 8 transposing LDS reads issued in stage 0; scaled q/k written transposed in place with b64 stores; stage-1 operands via tr reads
# baseline (speedup 1.0000x reference)
; #define LAS __attribute__((address_space(3)))
; __device__ __forceinline__ unsigned cvtpk(float lo, float hi) { f32x2 v = {lo, hi}; bf16x2_t b = __builtin_convertvector(v, bf16x2_t); return __builtin_bit_cast(unsigned, b); }
; __device__ __forceinline__ void gla_unit(LAS char* lds0, int b, int h, int dvh, bf16_t* Z, bf16_t* OT, const float* afw, const float* afb, const float* abw, const float* abb, bool dry) {
;     int tid = threadIdx.x; asm volatile("" : "+v"(tid)); const int lane = tid & 63, r32 = lane & 31, hi = lane >> 5; const int wid = __builtin_amdgcn_readfirstlane(tid >> 6);
;     const int dir = wid >> 2, wg = wid & 3, tg = tid & 255;
;     LAS char* lds = lds0 + dir * G_GROUP;
;     const int g16 = (lane >> 4) & 1, q4 = (lane & 15) >> 2, p4 = lane & 3;
;     const int I = wg >> 1, J = wg & 1;
;     const float* w2 = dir ? abw : afw; const float* bb = dir ? abb : afb;
;     bf16x8 w2b;
;     { u32x4 t; t.x = cvtpk(w2[(8 * hi + 0) * 256 + h * 64 + 32 * J + r32], w2[(8 * hi + 1) * 256 + h * 64 + 32 * J + r32]);
;       t.y = cvtpk(w2[(8 * hi + 2) * 256 + h * 64 + 32 * J + r32], w2[(8 * hi + 3) * 256 + h * 64 + 32 * J + r32]);
;       t.z = cvtpk(w2[(8 * hi + 4) * 256 + h * 64 + 32 * J + r32], w2[(8 * hi + 5) * 256 + h * 64 + 32 * J + r32]);
;       t.w = cvtpk(w2[(8 * hi + 6) * 256 + h * 64 + 32 * J + r32], w2[(8 * hi + 7) * 256 + h * 64 + 32 * J + r32]);
;       w2b = __builtin_bit_cast(bf16x8, t); }
;     const float bias = bb[h * 64 + 32 * J + r32];
;     const int zcol_a = dir ? ZAB : ZAF;
;     f32x16 S = {};
;     for (int i = tg; i < GARR / 4; i += 256) ((LAS unsigned*)(lds + G_SB))[i] = 0u;
;     u32x4 pq0, pq1, pk0, pk1, pv0, pv1; u32x2 pa;
;     const int lr = tg >> 3, lc = tg & 7, ar = tg >> 2, ac = tg & 3;
;     ...
;     GLA_PREFETCH(0);
.LBB0_401:
	v_mov_b32_e32 v6, v182
	s_bfe_u32 s8, s97, 0x20001
	v_readfirstlane_b32 s28, v6
	s_lshr_b32 s0, s28, 8
	s_mul_i32 s0, s0, 0x10a00
	s_add_i32 s76, s0, 0
	s_bfe_u32 s42, s28, 0x10006
	s_cmpk_lt_u32 s28, 0x100
	s_cselect_b64 s[0:1], -1, 0
	s_cmpk_gt_u32 s28, 0xff
	v_readlane_b32 s52, v254, 59
	s_cselect_b64 s[16:17], -1, 0
	s_and_b64 s[2:3], s[0:1], exec
	v_readlane_b32 s54, v254, 61
	v_readlane_b32 s58, v255, 1
	v_readlane_b32 s55, v254, 62
	v_readlane_b32 s59, v255, 2
	s_cselect_b32 s2, s54, s58
	s_cselect_b32 s3, s55, s59
	s_add_u32 s2, s2, s94
	s_addc_u32 s3, s3, s95
	v_readlane_b32 s56, v254, 63
	s_and_b64 s[14:15], s[0:1], exec
	v_readlane_b32 s44, v254, 55
	v_readlane_b32 s57, v255, 0
	v_readlane_b32 s45, v254, 56
	s_cselect_b32 s15, s56, s44
	v_readlane_b32 s24, v255, 36
	v_bfe_u32 v16, v6, 3, 5
	s_cselect_b32 s14, s57, s45
	v_readlane_b32 s25, v255, 37
	s_add_u32 s24, s15, s24
	v_and_b32_e32 v14, 31, v6
	v_bfe_u32 v15, v6, 5, 1
	v_xor_b32_e32 v0, 63, v16
	s_addc_u32 s25, s14, s25
	s_lshl_b32 s43, s42, 5
	v_cndmask_b32_e64 v114, v0, v16, s[0:1]
	v_lshlrev_b32_e32 v0, 11, v15
	s_lshl_b32 s77, s8, 6
	v_or_b32_e32 v18, s43, v14
	v_or3_b32 v0, v0, s77, v18
	v_lshlrev_b32_e32 v0, 2, v0
	v_lshl_add_u64 v[2:3], s[2:3], 0, v[0:1]
	global_load_dword v17, v0, s[2:3]
	global_load_dword v19, v0, s[2:3] offset:1024
	global_load_dword v21, v0, s[2:3] offset:2048
	s_nop 0
	global_load_dword v0, v0, s[2:3] offset:3072
	s_movk_i32 s2, 0x1000
	v_add_co_u32_e32 v2, vcc, s2, v2
	s_ashr_i32 s2, s97, 3
	s_nop 0
	v_addc_co_u32_e32 v3, vcc, 0, v3, vcc
	s_lshr_b32 s40, s28, 7
	s_bfe_u32 s84, s28, 0x10007
	global_load_dword v22, v[2:3], off
	global_load_dword v23, v[2:3], off offset:1024
	global_load_dword v24, v[2:3], off offset:2048
	s_nop 0
	global_load_dword v3, v[2:3], off offset:3072
	v_and_b32_e32 v2, 0xff, v6
	s_and_b64 s[14:15], s[0:1], exec
	v_lshrrev_b32_e32 v25, 5, v6
	v_bfe_u32 v26, v6, 2, 2
	v_and_b32_e32 v27, 16, v6
	v_and_b32_e32 v28, 3, v6
	v_and_b32_e32 v7, 7, v6
	v_bfe_u32 v29, v6, 2, 6
	v_xor_b32_e32 v6, 31, v16
	v_or_b32_e32 v8, 32, v16
	v_lshl_add_u32 v2, v2, 2, s76
	s_mul_hi_i32 s14, s2, 0x900
	s_mul_i32 s15, s2, 0x900
	s_movk_i32 s2, 0x380
	s_cselect_b32 s34, 0, 0xc0
	ds_write2st64_b32 v2, v1, v1 offset0:180 offset1:184
	ds_write2st64_b32 v2, v1, v1 offset0:188 offset1:192
	ds_write2st64_b32 v2, v1, v1 offset0:196 offset1:200
	ds_write2st64_b32 v2, v1, v1 offset0:204 offset1:208
	ds_write_b32 v2, v1 offset:54272
	v_cndmask_b32_e64 v118, v6, v8, s[0:1]
	v_or_b32_e32 v2, s77, v18
	s_cselect_b32 s28, s2, 0x3a0
	s_or_b32 s34, s34, s15
	v_mov_b64_e32 v[4:5], s[88:89]
	v_lshlrev_b32_e32 v2, 2, v2
	v_or_b32_e32 v6, s34, v114
	v_or_b32_e32 v8, s34, v118
	v_lshlrev_b32_e32 v20, 3, v7
	v_lshlrev_b32_e32 v116, 4, v7
	global_load_dword v2, v2, s[24:25]
	v_mad_u64_u32 v[6:7], s[24:25], v6, s13, v[4:5]
	v_mad_u64_u32 v[8:9], s[24:25], v8, s13, v[4:5]
	s_mov_b32 s3, s9
	s_lshl_b32 s2, s8, 7
	v_mad_i32_i24 v7, s14, v204, v7
	v_mad_i32_i24 v9, s14, v204, v9
	v_lshl_add_u64 v[10:11], v[6:7], 0, s[2:3]
	v_lshl_add_u64 v[12:13], v[8:9], 0, s[2:3]
	s_lshl_b32 s3, s97, 6
	s_lshl_b32 s8, s8, 8
	s_and_b32 s3, s3, 64
	s_mov_b32 s29, 0
	v_lshl_add_u64 v[6:7], v[6:7], 0, s[8:9]
	s_lshl_b32 s24, s3, 1
	s_mov_b32 s25, s9
	v_mov_b32_e32 v117, v1
	v_lshl_add_u64 v[6:7], v[6:7], 0, s[24:25]
	v_lshl_add_u64 v[8:9], v[8:9], 0, s[8:9]
	v_lshl_add_u64 v[10:11], v[10:11], 0, v[116:117]
	v_lshl_add_u64 v[12:13], v[12:13], 0, v[116:117]
	v_lshl_add_u64 v[6:7], v[6:7], 0, v[116:117]
	v_lshl_add_u64 v[8:9], v[8:9], 0, s[24:25]
	global_load_dwordx4 v[70:73], v[10:11], off offset:2048
	global_load_dwordx4 v[74:77], v[10:11], off offset:2560
	global_load_dwordx4 v[78:81], v[12:13], off offset:2048
	global_load_dwordx4 v[82:85], v[12:13], off offset:2560
	v_lshl_add_u64 v[8:9], v[8:9], 0, v[116:117]
	global_load_dwordx4 v[86:89], v[6:7], off offset:3072
	global_load_dwordx4 v[90:93], v[8:9], off offset:3072
	v_and_b32_e32 v6, 64, v203
	v_add_u32_e32 v6, 64, v6
	v_lshlrev_b32_e32 v30, 3, v15
	v_mov_b32_e32 v31, s76
	s_movk_i32 s44, 0x90
	v_mad_u32_u24 v136, v18, s44, v31
	v_or_b32_e32 v44, v30, v26
	v_readlane_b32 s46, v254, 57
	v_readlane_b32 s47, v254, 58
	v_mul_u32_u24_e32 v154, 0x90, v44
	v_or_b32_e32 v44, 16, v30
	v_or_b32_e32 v46, 32, v30
	v_or_b32_e32 v30, 48, v30
	v_readlane_b32 s53, v254, 60
	v_mad_u32_u24 v115, v16, s44, v31
	s_waitcnt vmcnt(0)
; #define LAS __attribute__((address_space(3)))
; __device__ __forceinline__ unsigned cvtpk(float lo, float hi) { f32x2 v = {lo, hi}; bf16x2_t b = __builtin_convertvector(v, bf16x2_t); return __builtin_bit_cast(unsigned, b); }
; __device__ __forceinline__ void gla_unit(LAS char* lds0, int b, int h, int dvh, bf16_t* Z, bf16_t* OT, const float* afw, const float* afb, const float* abw, const float* abb, bool dry) {
;     int tid = threadIdx.x; asm volatile("" : "+v"(tid)); const int lane = tid & 63, r32 = lane & 31, hi = lane >> 5; const int wid = __builtin_amdgcn_readfirstlane(tid >> 6);
;     const int dir = wid >> 2, wg = wid & 3, tg = tid & 255;
;     LAS char* lds = lds0 + dir * G_GROUP;
;     const int g16 = (lane >> 4) & 1, q4 = (lane & 15) >> 2, p4 = lane & 3;
;     const int I = wg >> 1, J = wg & 1;
;     const float* w2 = dir ? abw : afw; const float* bb = dir ? abb : afb;
;     bf16x8 w2b;
;     { u32x4 t; t.x = cvtpk(w2[(8 * hi + 0) * 256 + h * 64 + 32 * J + r32], w2[(8 * hi + 1) * 256 + h * 64 + 32 * J + r32]);
;       t.y = cvtpk(w2[(8 * hi + 2) * 256 + h * 64 + 32 * J + r32], w2[(8 * hi + 3) * 256 + h * 64 + 32 * J + r32]);
;       t.z = cvtpk(w2[(8 * hi + 4) * 256 + h * 64 + 32 * J + r32], w2[(8 * hi + 5) * 256 + h * 64 + 32 * J + r32]);
;       t.w = cvtpk(w2[(8 * hi + 6) * 256 + h * 64 + 32 * J + r32], w2[(8 * hi + 7) * 256 + h * 64 + 32 * J + r32]);
;       w2b = __builtin_bit_cast(bf16x8, t); }
;     const float bias = bb[h * 64 + 32 * J + r32];
;     const int zcol_a = dir ? ZAB : ZAF;
;     f32x16 S = {};
;     for (int i = tg; i < GARR / 4; i += 256) ((LAS unsigned*)(lds + G_SB))[i] = 0u;
;     u32x4 pq0, pq1, pk0, pk1, pv0, pv1; u32x2 pa;
;     const int lr = tg >> 3, lc = tg & 7, ar = tg >> 2, ac = tg & 3;
	v_cvt_pk_bf16_f32 v67, v21, v0
	v_xor_b32_e32 v0, 63, v29
	v_cndmask_b32_e64 v120, v0, v29, s[0:1]
	v_or_b32_e32 v0, s34, v120
	v_mad_u64_u32 v[4:5], s[34:35], v0, s13, v[4:5]
	v_mad_i32_i24 v5, s14, v204, v5
	v_lshl_add_u64 v[4:5], v[4:5], 0, s[28:29]
	v_lshlrev_b32_e32 v0, 3, v28
	v_lshl_add_u64 v[4:5], v[4:5], 0, v[0:1]
	global_load_dwordx2 v[126:127], v[4:5], off
	s_add_u32 s34, s88, s28
	s_addc_u32 s35, s89, 0
	v_lshl_add_u64 v[122:123], s[34:35], 0, v[0:1]
	v_readlane_b32 s34, v252, 21
	v_readlane_b32 s35, v252, 22
	s_add_u32 s8, s34, s8
	s_addc_u32 s25, s35, 0
	s_add_u32 s24, s8, s24
	s_addc_u32 s25, s25, 0
	v_lshl_add_u64 v[124:125], s[24:25], 0, v[116:117]
	s_add_i32 s24, s76, 0x10500
	s_lshl_b32 s28, s42, 7
	v_xor_b32_e32 v5, 32, v203
	s_lshl_b32 s25, s84, 8
	s_add_i32 s28, s24, s28
	s_lshl_b32 s8, s84, 5
	v_cmp_lt_i32_e32 vcc, v5, v6
	s_add_i32 s25, s28, s25
	v_cvt_pk_bf16_f32 v68, v22, v23
	v_cndmask_b32_e32 v5, v203, v5, vcc
	v_lshlrev_b32_e32 v6, 2, v18
	s_cmp_eq_u32 s84, 0
	v_lshl_or_b32 v23, v15, 2, s8
	v_lshl_add_u32 v21, v29, 5, s76
	v_lshlrev_b32_e32 v119, 2, v5
	v_lshlrev_b32_e32 v5, 2, v14
	v_add_u32_e32 v132, s24, v6
	s_cselect_b64 s[34:35], -1, 0
	s_add_i32 s24, s76, 0x10400
	v_mul_u32_u24_e32 v29, 0x48, v23
	v_cvt_pk_bf16_f32 v69, v24, v3
	v_lshlrev_b32_e32 v3, 2, v28
	v_or_b32_e32 v4, s8, v14
	v_add_u32_e32 v121, s25, v5
	v_lshlrev_b32_e32 v24, 1, v18
	s_cmp_le_u32 s42, s84
	s_movk_i32 s25, 0xff72
	v_lshlrev_b32_e32 v29, 1, v29
	v_lshl_add_u32 v22, v4, 5, s76
	v_lshlrev_b32_e32 v117, 4, v15
	v_add_u32_e32 v133, s28, v5
	v_bitop3_b32 v5, s40, 1, v25 bitop3:0xc8
	s_cselect_b64 s[78:79], -1, 0
	v_mad_u32_u24 v135, v4, s44, v31
	v_or3_b32 v4, v3, v27, s43
	v_mad_i32_i24 v25, v18, s25, v136
	v_lshl_add_u32 v238, v23, 1, v136
	v_add_u32_e32 v239, v136, v117
	s_lshl_b32 s25, s42, 6
	v_or3_b32 v3, v27, s8, v3
	v_add3_u32 v138, s76, v24, v29
	v_or_b32_e32 v29, 2, v23
	s_add_i32 s8, s76, 0x10420
	v_lshl_add_u32 v137, v4, 1, s76
	v_add_u32_e32 v222, v23, v26
	v_mul_u32_u24_e32 v222, 0x90, v222
	v_add_u32_e32 v222, v137, v222
	s_add_i32 s25, s76, s25
	v_lshl_add_u32 v27, v3, 1, s76
	v_or_b32_e32 v24, 1, v23
	v_or_b32_e32 v31, 3, v23
	v_or_b32_e32 v32, 8, v23
	v_or_b32_e32 v33, 9, v23
	v_or_b32_e32 v34, 10, v23
	v_or_b32_e32 v35, 11, v23
	v_or_b32_e32 v36, 16, v23
	v_or_b32_e32 v37, 17, v23
	v_or_b32_e32 v38, 18, v23
	v_or_b32_e32 v39, 19, v23
	v_or_b32_e32 v40, 24, v23
	v_or_b32_e32 v41, 25, v23
	v_or_b32_e32 v42, 26, v23
	v_or_b32_e32 v43, 27, v23
	v_lshlrev_b32_e32 v45, 1, v44
	v_or_b32_e32 v44, v44, v26
	v_lshlrev_b32_e32 v47, 1, v46
	v_or_b32_e32 v46, v46, v26
	v_or_b32_e32 v26, v30, v26
	v_cmp_lt_u32_e64 s[46:47], v29, v18
	v_add_u32_e32 v29, s8, v117
	s_add_i32 s8, s76, 0x10440
	s_add_i32 s76, s76, 0x10460
	v_cvt_pk_bf16_f32 v66, v17, v19
	v_add_u32_e32 v19, 0x1200, v115
	v_lshl_add_u32 v28, v14, 1, s25
	v_mul_u32_u24_e32 v44, 0x90, v44
	v_mul_u32_u24_e32 v46, 0x90, v46
	v_lshlrev_b32_e32 v48, 1, v30
	v_mul_u32_u24_e32 v26, 0x90, v26
	v_cmp_lt_u32_e64 s[42:43], v23, v18
	v_mul_u32_u24_e32 v23, 0x90, v23
	v_cmp_lt_u32_e64 s[44:45], v24, v18
	v_cmp_lt_u32_e64 s[50:51], v31, v18
	v_cmp_lt_u32_e64 s[52:53], v32, v18
	v_cmp_lt_u32_e64 s[54:55], v33, v18
	v_cmp_lt_u32_e64 s[56:57], v34, v18
	v_cmp_lt_u32_e64 s[58:59], v35, v18
	v_cmp_lt_u32_e64 s[60:61], v36, v18
	v_cmp_lt_u32_e64 s[62:63], v37, v18
	v_cmp_lt_u32_e64 s[64:65], v38, v18
	v_cmp_lt_u32_e64 s[66:67], v39, v18
	v_cmp_lt_u32_e64 s[68:69], v40, v18
	v_cmp_lt_u32_e64 s[70:71], v41, v18
	v_cmp_lt_u32_e64 s[72:73], v42, v18
	v_cmp_lt_u32_e64 s[74:75], v43, v18
	s_lshl_b32 s25, s84, 7
	v_add_u32_e32 v24, s24, v117
	v_add_u32_e32 v30, s8, v117
	v_add_u32_e32 v31, s76, v117
	v_mov_b32_e32 v18, 0
	v_cmp_eq_u32_e64 s[38:39], 0, v15
	v_cmp_eq_u32_e64 s[40:41], 0, v5
	v_add_u32_e32 v134, s24, v6
	v_mov_b32_e32 v3, v2
	v_mov_b32_e32 v4, v2
	v_mov_b32_e32 v5, v2
	v_mov_b32_e32 v6, v2
	v_mov_b32_e32 v7, v2
	v_mov_b32_e32 v8, v2
	v_mov_b32_e32 v9, v2
	v_mov_b32_e32 v10, v2
	v_mov_b32_e32 v11, v2
	v_mov_b32_e32 v12, v2
	v_mov_b32_e32 v13, v2
	v_mov_b32_e32 v14, v2
	v_mov_b32_e32 v15, v2
	v_mov_b32_e32 v16, v2
	v_mov_b32_e32 v17, v2
	v_add_u32_e32 v139, 0x90, v138
	s_waitcnt lgkmcnt(5)
	v_add_u32_e32 v140, 0x120, v138
	v_add_u32_e32 v141, 0x1b0, v138
	v_add_u32_e32 v142, 0x480, v138
	v_add_u32_e32 v143, 0x510, v138
	v_add_u32_e32 v144, 0x5a0, v138
	v_add_u32_e32 v145, 0x630, v138
	v_add_u32_e32 v146, 0x900, v138
	v_add_u32_e32 v147, 0x990, v138
	v_add_u32_e32 v148, 0xa20, v138
	v_add_u32_e32 v149, 0xab0, v138
	v_add_u32_e32 v150, 0xd80, v138
	v_add_u32_e32 v151, 0xe10, v138
	v_add_u32_e32 v152, 0xea0, v138
	v_add_u32_e32 v153, 0xf30, v138
	v_add_u32_e32 v155, v21, v0
	s_lshl_b32 s8, s77, 1
	v_lshlrev_b32_e32 v0, 1, v20
	s_lshl_b32 s24, s2, 1
	s_lshl_b32 s84, s3, 1
	v_add_u32_e32 v156, v22, v117
	v_add_u32_e32 v157, v137, v44
	v_add_u32_e32 v158, v137, v46
	v_add_u32_e32 v159, v137, v26
	v_add_u32_e32 v160, v25, v23
	v_add_u32_e32 v161, v28, v23
	v_add_u32_e32 v162, s25, v24
	v_add_u32_e32 v163, s25, v29
	v_add_u32_e32 v164, s25, v30
	v_add_u32_e32 v165, s25, v31
	v_add_u32_e32 v166, v27, v154
	v_add_u32_e32 v167, v19, v116
	v_add_u32_e32 v168, v135, v45
	v_add_u32_e32 v169, v135, v47
	v_add_u32_e32 v170, v135, v48
	s_mov_b32 s76, s29
	v_mov_b32_e32 v19, v18
	v_mov_b32_e32 v20, v18
	v_mov_b32_e32 v21, v18
	v_mov_b32_e32 v22, v18
	v_mov_b32_e32 v23, v18
	v_mov_b32_e32 v24, v18
	v_mov_b32_e32 v25, v18
	v_mov_b32_e32 v26, v18
	v_mov_b32_e32 v27, v18
	v_mov_b32_e32 v28, v18
	v_mov_b32_e32 v29, v18
	v_mov_b32_e32 v30, v18
	v_mov_b32_e32 v31, v18
	v_mov_b32_e32 v32, v18
	v_mov_b32_e32 v33, v18
	s_branch .LBB0_403

; #define LAS __attribute__((address_space(3)))
; __device__ __forceinline__ float fexp(float x) { return __builtin_amdgcn_exp2f(x * 1.4426950408889634f); }
; __device__ __forceinline__ void gla_unit(LAS char* lds0, int b, int h, int dvh, bf16_t* Z, bf16_t* OT, const float* afw, const float* afb, const float* abw, const float* abb, bool dry) {
;     ...
;         {
;             f32x16 zc;
; #pragma unroll
;             for (int r = 0; r < 16; ++r) zc[r] = bias;
;             const bf16x8 a = *(const LAS bf16x8*)(lds + G_A16 + (32 * I + r32) * 32 + hi * 16);
;             zc = __builtin_amdgcn_mfma_f32_32x32x16_bf16(a, w2b, zc, 0, 0, 0);
; #pragma unroll
;             for (int r = 0; r < 16; ++r) { const float z = zc[r]; cs[r] = (fminf(z, 0.f) - __logf(1.f + fexp(-fabsf(z)))) * (1.f / 16.f); }
;         }
; #pragma unroll
;         for (int g = 0; g < 4; ++g) { cs[4 * g + 1] += cs[4 * g]; cs[4 * g + 2] += cs[4 * g + 1]; cs[4 * g + 3] += cs[4 * g + 2]; }
;         float run = 0.f;
; #pragma unroll
;         for (int g = 0; g < 4; ++g) {
;             const float mine = cs[4 * g + 3]; const float oth = __shfl_xor(mine, 32);
;             const float off = run + (hi ? oth : 0.f);
; #pragma unroll
;             for (int j = 0; j < 4; ++j) cs[4 * g + j] += off;
;             run += mine + oth;
;         }
.LBB0_412:
	ds_read_b128 v[50:53], v156 offset:64512
	s_waitcnt lgkmcnt(0)
	v_mfma_f32_32x32x16_bf16 v[34:49], v[50:53], v[66:69], v[2:17]
	ds_read_b64_tr_b16 v[206:207], v222 offset:0
	ds_read_b64_tr_b16 v[208:209], v222 offset:1152
	ds_read_b64_tr_b16 v[210:211], v222 offset:2304
	ds_read_b64_tr_b16 v[212:213], v222 offset:3456
	ds_read_b64_tr_b16 v[214:215], v222 offset:9216
	ds_read_b64_tr_b16 v[216:217], v222 offset:10368
	ds_read_b64_tr_b16 v[218:219], v222 offset:11520
	ds_read_b64_tr_b16 v[220:221], v222 offset:12672
	s_nop 11
	v_max_f32_e32 v50, v34, v34
	v_mul_f32_e64 v34, |v34|, s33
	v_exp_f32_e32 v34, v34
	v_min_f32_e32 v50, 0, v50
	v_add_f32_e32 v34, 1.0, v34
	v_log_f32_e32 v34, v34
	s_nop 0
	v_mul_f32_e32 v51, 0x3f317217, v34
	v_fma_f32 v51, v34, s19, -v51
	v_fmac_f32_e32 v51, 0x3377d1cf, v34
	v_fmac_f32_e32 v51, 0x3f317217, v34
	v_sub_f32_e32 v34, v50, v51
	v_max_f32_e32 v50, v35, v35
	v_mul_f32_e64 v35, |v35|, s33
	v_exp_f32_e32 v35, v35
	v_min_f32_e32 v50, 0, v50
	v_mul_f32_e32 v34, 0x3d800000, v34
	v_add_f32_e32 v35, 1.0, v35
	v_log_f32_e32 v35, v35
	s_nop 0
	v_mul_f32_e32 v51, 0x3f317217, v35
	v_fma_f32 v51, v35, s19, -v51
	v_fmac_f32_e32 v51, 0x3377d1cf, v35
	v_fmac_f32_e32 v51, 0x3f317217, v35
	v_sub_f32_e32 v35, v50, v51
	v_max_f32_e32 v50, v36, v36
	v_mul_f32_e64 v36, |v36|, s33
	v_exp_f32_e32 v36, v36
	v_min_f32_e32 v50, 0, v50
	v_add_f32_e32 v36, 1.0, v36
	v_log_f32_e32 v36, v36
	s_nop 0
	v_mul_f32_e32 v51, 0x3f317217, v36
	v_fma_f32 v51, v36, s19, -v51
	v_fmac_f32_e32 v51, 0x3377d1cf, v36
	v_fmac_f32_e32 v51, 0x3f317217, v36
	v_sub_f32_e32 v36, v50, v51
	v_max_f32_e32 v50, v37, v37
	v_mul_f32_e64 v37, |v37|, s33
	v_exp_f32_e32 v37, v37
	v_min_f32_e32 v50, 0, v50
	v_add_f32_e32 v37, 1.0, v37
	v_log_f32_e32 v37, v37
	s_nop 0
	v_mul_f32_e32 v51, 0x3f317217, v37
	v_fma_f32 v51, v37, s19, -v51
	v_fmac_f32_e32 v51, 0x3377d1cf, v37
	v_fmac_f32_e32 v51, 0x3f317217, v37
	v_sub_f32_e32 v50, v50, v51
	v_max_f32_e32 v37, v38, v38
	v_mul_f32_e64 v38, |v38|, s33
	v_exp_f32_e32 v38, v38
	v_min_f32_e32 v37, 0, v37
	v_add_f32_e32 v38, 1.0, v38
	v_log_f32_e32 v38, v38
	s_nop 0
	v_mul_f32_e32 v51, 0x3f317217, v38
	v_fma_f32 v51, v38, s19, -v51
	v_fmac_f32_e32 v51, 0x3377d1cf, v38
	v_fmac_f32_e32 v51, 0x3f317217, v38
	v_sub_f32_e32 v37, v37, v51
	v_max_f32_e32 v38, v39, v39
	v_mul_f32_e64 v39, |v39|, s33
	v_exp_f32_e32 v39, v39
	v_min_f32_e32 v38, 0, v38
	v_mul_f32_e32 v37, 0x3d800000, v37
	v_add_f32_e32 v39, 1.0, v39
	v_log_f32_e32 v39, v39
	s_nop 0
	v_mul_f32_e32 v51, 0x3f317217, v39
	v_fma_f32 v51, v39, s19, -v51
	v_fmac_f32_e32 v51, 0x3377d1cf, v39
	v_fmac_f32_e32 v51, 0x3f317217, v39
	v_sub_f32_e32 v38, v38, v51
	v_max_f32_e32 v39, v40, v40
	v_mul_f32_e64 v40, |v40|, s33
	v_exp_f32_e32 v40, v40
	v_min_f32_e32 v39, 0, v39
	v_add_f32_e32 v40, 1.0, v40
	v_log_f32_e32 v40, v40
	s_nop 0
	v_mul_f32_e32 v51, 0x3f317217, v40
	v_fma_f32 v51, v40, s19, -v51
	v_fmac_f32_e32 v51, 0x3377d1cf, v40
	v_fmac_f32_e32 v51, 0x3f317217, v40
	v_sub_f32_e32 v39, v39, v51
	v_max_f32_e32 v40, v41, v41
	v_mul_f32_e64 v41, |v41|, s33
	v_exp_f32_e32 v41, v41
	v_min_f32_e32 v40, 0, v40
	v_add_f32_e32 v41, 1.0, v41
	v_log_f32_e32 v41, v41
	s_nop 0
	v_mul_f32_e32 v51, 0x3f317217, v41
	v_fma_f32 v51, v41, s19, -v51
	v_fmac_f32_e32 v51, 0x3377d1cf, v41
	v_fmac_f32_e32 v51, 0x3f317217, v41
	v_sub_f32_e32 v41, v40, v51
	v_max_f32_e32 v40, v42, v42
	v_mul_f32_e64 v42, |v42|, s33
	v_exp_f32_e32 v42, v42
	v_min_f32_e32 v40, 0, v40
	v_add_f32_e32 v42, 1.0, v42
	v_log_f32_e32 v42, v42
	s_nop 0
	v_mul_f32_e32 v51, 0x3f317217, v42
	v_fma_f32 v51, v42, s19, -v51
	v_fmac_f32_e32 v51, 0x3377d1cf, v42
	v_fmac_f32_e32 v51, 0x3f317217, v42
	v_sub_f32_e32 v40, v40, v51
	v_max_f32_e32 v42, v43, v43
	v_mul_f32_e64 v43, |v43|, s33
	v_exp_f32_e32 v43, v43
	v_min_f32_e32 v42, 0, v42
	v_mul_f32_e32 v40, 0x3d800000, v40
	v_add_f32_e32 v43, 1.0, v43
	v_log_f32_e32 v43, v43
	s_nop 0
	v_mul_f32_e32 v51, 0x3f317217, v43
	v_fma_f32 v51, v43, s19, -v51
	v_fmac_f32_e32 v51, 0x3377d1cf, v43
	v_fmac_f32_e32 v51, 0x3f317217, v43
	v_sub_f32_e32 v51, v42, v51
	v_mul_f32_e64 v43, |v44|, s33
	v_exp_f32_e32 v43, v43
	v_max_f32_e32 v42, v44, v44
	v_min_f32_e32 v42, 0, v42
	v_add_f32_e32 v43, 1.0, v43
	v_log_f32_e32 v43, v43
	s_nop 0
	v_mul_f32_e32 v44, 0x3f317217, v43
	v_fma_f32 v44, v43, s19, -v44
	v_fmac_f32_e32 v44, 0x3377d1cf, v43
	v_fmac_f32_e32 v44, 0x3f317217, v43
	v_sub_f32_e32 v52, v42, v44
	v_mul_f32_e64 v43, |v45|, s33
	v_exp_f32_e32 v43, v43
	v_max_f32_e32 v42, v45, v45
	v_min_f32_e32 v42, 0, v42
	v_add_f32_e32 v43, 1.0, v43
	v_log_f32_e32 v43, v43
	s_nop 0
	v_mul_f32_e32 v44, 0x3f317217, v43
	v_fma_f32 v44, v43, s19, -v44
	v_fmac_f32_e32 v44, 0x3377d1cf, v43
	v_fmac_f32_e32 v44, 0x3f317217, v43
	v_sub_f32_e32 v53, v42, v44
	v_mul_f32_e64 v43, |v46|, s33
	v_exp_f32_e32 v43, v43
	v_max_f32_e32 v42, v46, v46
	v_min_f32_e32 v42, 0, v42
	v_add_f32_e32 v43, 1.0, v43
	v_log_f32_e32 v43, v43
	s_nop 0
	v_mul_f32_e32 v44, 0x3f317217, v43
	v_fma_f32 v44, v43, s19, -v44
	v_fmac_f32_e32 v44, 0x3377d1cf, v43
	v_fmac_f32_e32 v44, 0x3f317217, v43
	v_sub_f32_e32 v42, v42, v44
	v_mul_f32_e64 v43, |v47|, s33
	v_exp_f32_e32 v43, v43
	v_mul_f32_e32 v46, 0x3d800000, v42
	v_max_f32_e32 v42, v47, v47
	v_min_f32_e32 v42, 0, v42
	v_add_f32_e32 v43, 1.0, v43
	v_log_f32_e32 v43, v43
	s_nop 0
	v_mul_f32_e32 v44, 0x3f317217, v43
	v_fma_f32 v44, v43, s19, -v44
	v_fmac_f32_e32 v44, 0x3377d1cf, v43
	v_fmac_f32_e32 v44, 0x3f317217, v43
	v_sub_f32_e32 v47, v42, v44
	v_mul_f32_e64 v43, |v48|, s33
	v_exp_f32_e32 v43, v43
	v_max_f32_e32 v42, v48, v48
	v_min_f32_e32 v42, 0, v42
	v_add_f32_e32 v43, 1.0, v43
	v_log_f32_e32 v43, v43
	s_nop 0
	v_mul_f32_e32 v44, 0x3f317217, v43
	v_fma_f32 v44, v43, s19, -v44
	v_fmac_f32_e32 v44, 0x3377d1cf, v43
	v_fmac_f32_e32 v44, 0x3f317217, v43
	v_sub_f32_e32 v54, v42, v44
	v_mul_f32_e64 v43, |v49|, s33
	v_exp_f32_e32 v43, v43
	v_max_f32_e32 v42, v49, v49
	v_min_f32_e32 v42, 0, v42
	v_add_f32_e32 v43, 1.0, v43
	v_log_f32_e32 v43, v43
	s_nop 0
	v_mul_f32_e32 v44, 0x3f317217, v43
	v_fma_f32 v44, v43, s19, -v44
	v_fmac_f32_e32 v44, 0x3377d1cf, v43
	v_fmac_f32_e32 v44, 0x3f317217, v43
	v_mov_b32_e32 v43, v44
	v_fmamk_f32 v44, v35, 0x3d800000, v34
	v_sub_f32_e32 v55, v42, v43
	v_fmamk_f32 v45, v36, 0x3d800000, v44
	v_fmamk_f32 v42, v38, 0x3d800000, v37
	v_fmamk_f32 v49, v50, 0x3d800000, v45
	v_fmamk_f32 v43, v39, 0x3d800000, v42
	v_fmamk_f32 v38, v51, 0x3d800000, v40
	v_fmamk_f32 v41, v41, 0x3d800000, v43
	v_fmamk_f32 v39, v52, 0x3d800000, v38
	v_fmamk_f32 v35, v47, 0x3d800000, v46
	ds_bpermute_b32 v51, v119, v49
	v_fmamk_f32 v48, v53, 0x3d800000, v39
	v_fmamk_f32 v36, v54, 0x3d800000, v35
	ds_bpermute_b32 v53, v119, v41
	v_fmamk_f32 v47, v55, 0x3d800000, v36
	ds_bpermute_b32 v55, v119, v48
	ds_bpermute_b32 v56, v119, v47
	s_waitcnt lgkmcnt(3)
; #define LAS __attribute__((address_space(3)))
; __device__ __forceinline__ bf16_t f2bf(float f) { return (bf16_t)(cvtpk(f, 0.f) & 0xffffu); }
; __device__ __forceinline__ float bf2f(bf16_t b) { return __uint_as_float(((unsigned)b) << 16); }
; __device__ __forceinline__ float fexp(float x) { return __builtin_amdgcn_exp2f(x * 1.4426950408889634f); }
; __device__ __forceinline__ float frcp(float x) { return __builtin_amdgcn_rcpf(x); }
; __device__ __forceinline__ int crow(int r, int hi) { return (r & 3) + 8 * (r >> 2) + 4 * hi; }
; __device__ __forceinline__ void gla_unit(LAS char* lds0, int b, int h, int dvh, bf16_t* Z, bf16_t* OT, const float* afw, const float* afb, const float* abw, const float* abb, bool dry) {
;     ...
;             const float mine = cs[4 * g + 3]; const float oth = __shfl_xor(mine, 32);
;             const float off = run + (hi ? oth : 0.f);
; #pragma unroll
;             for (int j = 0; j < 4; ++j) cs[4 * g + j] += off;
;             run += mine + oth;
;         }
;         if (hi == 0) ((LAS float*)(lds + G_TOT))[I * 64 + 32 * J + r32] = run;
;         asm volatile("s_waitcnt lgkmcnt(0)\n\ts_barrier" ::: "memory");
;         const float t0v = ((LAS float*)(lds + G_TOT))[32 * J + r32], t1v = ((LAS float*)(lds + G_TOT))[64 + 32 * J + r32];
;         const float pre = I ? t0v : 0.f, tot = t0v + t1v;
;         const float etot = fexp(tot);
; #pragma unroll
;         for (int r = 0; r < 16; ++r) {
;             const int ii = 32 * I + crow(r, hi), dd = 32 * J + r32; const float eb = fexp(pre + cs[r]); const float ieb = frcp(eb);
;             LAS bf16_t* qp = (LAS bf16_t*)(lds + G_Q) + ii * (GP / 2) + dd; LAS bf16_t* kp = (LAS bf16_t*)(lds + G_K) + ii * (GP / 2) + dd;
;             const float qv = bf2f(*qp), kv = bf2f(*kp);
;             *qp = f2bf(qv * eb); *kp = f2bf(kv * ieb);
;             ((LAS bf16_t*)(lds + G_KD))[ii * (GP / 2) + dd] = f2bf(kv * ieb * etot);
;         }
	v_add_f32_e32 v50, v49, v51
	v_add_f32_e32 v50, 0, v50
	s_waitcnt lgkmcnt(2)
	v_add_f32_e32 v52, v41, v53
	v_add_f32_e32 v52, v52, v50
	s_waitcnt lgkmcnt(1)
	v_add_f32_e32 v54, v48, v55
	v_add_f32_e32 v54, v54, v52
	s_and_saveexec_b64 s[76:77], s[38:39]
	s_cbranch_execz .LBB0_414
	s_waitcnt lgkmcnt(0)
	v_add_f32_e32 v57, v47, v56
	v_add_f32_e32 v57, v57, v54
	ds_write_b32 v121, v57
.LBB0_414:
	s_or_b64 exec, exec, s[76:77]
	v_add_f32_e32 v51, 0, v51
	v_cndmask_b32_e64 v51, v51, 0, s[38:39]
	v_add_f32_e32 v57, v51, v34
	v_cndmask_b32_e64 v34, v53, 0, s[38:39]
	v_add_f32_e32 v34, v34, v50
	v_add_f32_e32 v58, v51, v44
	v_add_f32_e32 v59, v51, v45
	v_add_f32_e32 v49, v51, v49
	v_add_f32_e32 v50, v37, v34
	v_add_f32_e32 v51, v42, v34
	v_add_f32_e32 v45, v43, v34
	v_add_f32_e32 v44, v41, v34
	v_cndmask_b32_e64 v34, v55, 0, s[38:39]
	v_add_f32_e32 v34, v34, v52
	v_add_f32_e32 v43, v40, v34
	v_add_f32_e32 v42, v38, v34
	v_add_f32_e32 v41, v39, v34
	v_add_f32_e32 v40, v48, v34
	s_waitcnt lgkmcnt(0)
	v_cndmask_b32_e64 v34, v56, 0, s[38:39]
	v_add_f32_e32 v34, v34, v54
	s_waitcnt lgkmcnt(0)
	s_barrier
	v_add_f32_e32 v39, v46, v34
	v_add_f32_e32 v38, v35, v34
	ds_read_b32 v35, v132
	ds_read_b32 v46, v133 offset:256
	s_waitcnt lgkmcnt(0)
	v_add_f32_e32 v36, v36, v34
	v_cndmask_b32_e64 v37, v35, 0, s[34:35]
	v_add_f32_e32 v35, v35, v46
	v_add_f32_e32 v46, v57, v37
	v_mul_f32_e32 v46, 0x3fb8aa3b, v46
	v_exp_f32_e32 v46, v46
	v_add_f32_e32 v34, v47, v34
	v_mul_f32_e32 v35, 0x3fb8aa3b, v35
	v_exp_f32_e32 v35, v35
	v_rcp_f32_e32 v47, v46
	v_lshlrev_b32_e32 v48, 16, v206
	v_mul_f32_e32 v223, v46, v48
	v_lshlrev_b32_e32 v52, 16, v214
	v_mul_f32_e32 v224, v47, v52
	v_mul_f32_e32 v240, v35, v224
	v_add_f32_e32 v46, v58, v37
	v_mul_f32_e32 v46, 0x3fb8aa3b, v46
	v_exp_f32_e32 v46, v46
	v_rcp_f32_e32 v47, v46
	v_add_f32_e32 v45, v45, v37
	v_and_b32_e32 v48, 0xffff0000, v206
	v_mul_f32_e32 v46, v46, v48
	v_and_b32_e32 v52, 0xffff0000, v214
	v_cvt_pk_bf16_f32 v226, v223, v46
	v_mul_f32_e32 v46, v47, v52
	v_cvt_pk_bf16_f32 v228, v224, v46
	v_mul_f32_e32 v46, v35, v46
	v_cvt_pk_bf16_f32 v242, v240, v46
	v_add_f32_e32 v46, v59, v37
	v_mul_f32_e32 v46, 0x3fb8aa3b, v46
	v_exp_f32_e32 v46, v46
	v_rcp_f32_e32 v47, v46
	v_mul_f32_e32 v45, 0x3fb8aa3b, v45
	v_lshlrev_b32_e32 v48, 16, v207
	v_mul_f32_e32 v223, v46, v48
	v_lshlrev_b32_e32 v52, 16, v215
	v_mul_f32_e32 v224, v47, v52
	v_mul_f32_e32 v240, v35, v224
	v_add_f32_e32 v46, v49, v37
	v_mul_f32_e32 v46, 0x3fb8aa3b, v46
	v_exp_f32_e32 v46, v46
	v_rcp_f32_e32 v47, v46
	v_exp_f32_e32 v45, v45
	v_and_b32_e32 v48, 0xffff0000, v207
	v_mul_f32_e32 v46, v46, v48
	v_and_b32_e32 v49, 0xffff0000, v215
	v_cvt_pk_bf16_f32 v227, v223, v46
	ds_write_b64 v238, v[226:227] offset:0
	v_mul_f32_e32 v46, v47, v49
	v_cvt_pk_bf16_f32 v229, v224, v46
	v_mul_f32_e32 v46, v35, v46
	v_cvt_pk_bf16_f32 v243, v240, v46
	ds_write_b64 v238, v[242:243] offset:18432
	v_add_f32_e32 v46, v50, v37
	v_mul_f32_e32 v46, 0x3fb8aa3b, v46
	v_exp_f32_e32 v46, v46
	ds_write_b64 v238, v[228:229] offset:9216
	v_rcp_f32_e32 v47, v46
	v_add_f32_e32 v44, v44, v37
	v_lshlrev_b32_e32 v48, 16, v208
	v_mul_f32_e32 v223, v46, v48
	v_lshlrev_b32_e32 v49, 16, v216
	v_mul_f32_e32 v224, v47, v49
	v_mul_f32_e32 v240, v35, v224
	v_add_f32_e32 v46, v51, v37
	v_mul_f32_e32 v46, 0x3fb8aa3b, v46
	v_exp_f32_e32 v46, v46
	v_rcp_f32_e32 v47, v46
	v_mul_f32_e32 v44, 0x3fb8aa3b, v44
	v_and_b32_e32 v48, 0xffff0000, v208
	v_mul_f32_e32 v46, v46, v48
	v_and_b32_e32 v49, 0xffff0000, v216
	v_cvt_pk_bf16_f32 v226, v223, v46
	v_mul_f32_e32 v46, v47, v49
	v_cvt_pk_bf16_f32 v228, v224, v46
	v_mul_f32_e32 v46, v35, v46
	v_cvt_pk_bf16_f32 v242, v240, v46
	v_rcp_f32_e32 v46, v45
	v_lshlrev_b32_e32 v47, 16, v209
	v_mul_f32_e32 v223, v45, v47
	v_lshlrev_b32_e32 v48, 16, v217
	v_mul_f32_e32 v224, v46, v48
	v_mul_f32_e32 v240, v35, v224
	v_exp_f32_e32 v44, v44
	v_add_f32_e32 v43, v43, v37
	v_rcp_f32_e32 v45, v44
	v_mul_f32_e32 v43, 0x3fb8aa3b, v43
	v_and_b32_e32 v46, 0xffff0000, v209
	v_mul_f32_e32 v44, v44, v46
	v_and_b32_e32 v47, 0xffff0000, v217
	v_cvt_pk_bf16_f32 v227, v223, v44
	ds_write_b64 v238, v[226:227] offset:16
	v_mul_f32_e32 v44, v45, v47
	v_cvt_pk_bf16_f32 v229, v224, v44
	v_mul_f32_e32 v44, v35, v44
	v_cvt_pk_bf16_f32 v243, v240, v44
	ds_write_b64 v238, v[228:229] offset:9232
	ds_write_b64 v238, v[242:243] offset:18448
	v_exp_f32_e32 v43, v43
	v_add_f32_e32 v42, v42, v37
	v_rcp_f32_e32 v44, v43
	v_mul_f32_e32 v42, 0x3fb8aa3b, v42
	v_lshlrev_b32_e32 v45, 16, v210
	v_mul_f32_e32 v223, v43, v45
	v_lshlrev_b32_e32 v46, 16, v218
	v_mul_f32_e32 v224, v44, v46
	v_mul_f32_e32 v240, v35, v224
	v_exp_f32_e32 v42, v42
	v_add_f32_e32 v41, v41, v37
	v_rcp_f32_e32 v43, v42
	v_mul_f32_e32 v41, 0x3fb8aa3b, v41
	v_and_b32_e32 v44, 0xffff0000, v210
	v_mul_f32_e32 v42, v42, v44
	v_and_b32_e32 v45, 0xffff0000, v218
	v_cvt_pk_bf16_f32 v226, v223, v42
	v_mul_f32_e32 v42, v43, v45
	v_cvt_pk_bf16_f32 v228, v224, v42
	v_mul_f32_e32 v42, v35, v42
	v_cvt_pk_bf16_f32 v242, v240, v42
	v_exp_f32_e32 v41, v41
	v_add_f32_e32 v40, v40, v37
	v_rcp_f32_e32 v42, v41
	v_mul_f32_e32 v40, 0x3fb8aa3b, v40
	v_lshlrev_b32_e32 v43, 16, v211
	v_mul_f32_e32 v223, v41, v43
	v_lshlrev_b32_e32 v44, 16, v219
	v_mul_f32_e32 v224, v42, v44
	v_mul_f32_e32 v240, v35, v224
	v_exp_f32_e32 v40, v40
	v_add_f32_e32 v39, v39, v37
	v_rcp_f32_e32 v41, v40
	v_mul_f32_e32 v39, 0x3fb8aa3b, v39
	v_and_b32_e32 v42, 0xffff0000, v211
	v_mul_f32_e32 v40, v40, v42
	v_and_b32_e32 v43, 0xffff0000, v219
	v_cvt_pk_bf16_f32 v227, v223, v40
	ds_write_b64 v238, v[226:227] offset:32
	v_mul_f32_e32 v40, v41, v43
	v_cvt_pk_bf16_f32 v229, v224, v40
	v_mul_f32_e32 v40, v35, v40
; #define LAS __attribute__((address_space(3)))
; __device__ __forceinline__ bf16_t f2bf(float f) { return (bf16_t)(cvtpk(f, 0.f) & 0xffffu); }
; __device__ __forceinline__ float bf2f(bf16_t b) { return __uint_as_float(((unsigned)b) << 16); }
; __device__ __forceinline__ float fexp(float x) { return __builtin_amdgcn_exp2f(x * 1.4426950408889634f); }
; __device__ __forceinline__ float frcp(float x) { return __builtin_amdgcn_rcpf(x); }
; __device__ __forceinline__ int crow(int r, int hi) { return (r & 3) + 8 * (r >> 2) + 4 * hi; }
; __device__ __forceinline__ void gla_unit(LAS char* lds0, int b, int h, int dvh, bf16_t* Z, bf16_t* OT, const float* afw, const float* afb, const float* abw, const float* abb, bool dry) {
;     ...
;             const int ii = 32 * I + crow(r, hi), dd = 32 * J + r32; const float eb = fexp(pre + cs[r]); const float ieb = frcp(eb);
;             LAS bf16_t* qp = (LAS bf16_t*)(lds + G_Q) + ii * (GP / 2) + dd; LAS bf16_t* kp = (LAS bf16_t*)(lds + G_K) + ii * (GP / 2) + dd;
;             const float qv = bf2f(*qp), kv = bf2f(*kp);
;             *qp = f2bf(qv * eb); *kp = f2bf(kv * ieb);
;             ((LAS bf16_t*)(lds + G_KD))[ii * (GP / 2) + dd] = f2bf(kv * ieb * etot);
;         }
;         if (I == 0 && hi == 0) ((LAS float*)(lds + G_DEC))[32 * J + r32] = etot;
;         asm volatile("s_waitcnt lgkmcnt(0)\n\ts_barrier" ::: "memory");
;         f32x16 oacc = {};
;         {
;             f32x16 Ac = {};
;             if (J <= I) {
; #pragma unroll
;                 for (int k = 0; k < 4; ++k) {
;                     const bf16x8 a = *(const LAS bf16x8*)(lds + G_Q + (32 * I + r32) * GP + (16 * k + 8 * hi) * 2);
;                     const bf16x8 bq = *(const LAS bf16x8*)(lds + G_K + (32 * J + r32) * GP + (16 * k + 8 * hi) * 2);
;                     Ac = __builtin_amdgcn_mfma_f32_32x32x16_bf16(a, bq, Ac, 0, 0, 0);
;                 }
;             }
; #pragma unroll
;             for (int k = 0; k < 4; ++k) {
;                 const bf16x8 a = *(const LAS bf16x8*)(lds + G_Q + (32 * I + r32) * GP + (16 * k + 8 * hi) * 2);
;                 const LAS char* sp = lds + G_SB + (16 * k + 8 * hi + q4) * GP + (32 * J + 16 * g16 + 4 * p4) * 2;
;                 const s16x4 l0 = trread(sp), l1 = trread(sp + 4 * GP);
;                 oacc = __builtin_amdgcn_mfma_f32_32x32x16_bf16(a, MK8(l0, l1), oacc, 0, 0, 0);
;             }
	v_cvt_pk_bf16_f32 v243, v240, v40
	ds_write_b64 v238, v[228:229] offset:9248
	ds_write_b64 v238, v[242:243] offset:18464
	v_exp_f32_e32 v39, v39
	v_add_f32_e32 v38, v38, v37
	v_rcp_f32_e32 v40, v39
	v_mul_f32_e32 v38, 0x3fb8aa3b, v38
	v_lshlrev_b32_e32 v41, 16, v212
	v_mul_f32_e32 v223, v39, v41
	v_lshlrev_b32_e32 v42, 16, v220
	v_mul_f32_e32 v224, v40, v42
	v_mul_f32_e32 v240, v35, v224
	v_exp_f32_e32 v38, v38
	v_add_f32_e32 v36, v36, v37
	v_rcp_f32_e32 v39, v38
	v_mul_f32_e32 v36, 0x3fb8aa3b, v36
	v_and_b32_e32 v40, 0xffff0000, v212
	v_mul_f32_e32 v38, v38, v40
	v_and_b32_e32 v41, 0xffff0000, v220
	v_cvt_pk_bf16_f32 v226, v223, v38
	v_mul_f32_e32 v38, v39, v41
	v_cvt_pk_bf16_f32 v228, v224, v38
	v_mul_f32_e32 v38, v35, v38
	v_cvt_pk_bf16_f32 v242, v240, v38
	v_exp_f32_e32 v36, v36
	v_add_f32_e32 v34, v34, v37
	v_rcp_f32_e32 v38, v36
	v_mul_f32_e32 v34, 0x3fb8aa3b, v34
	v_lshlrev_b32_e32 v39, 16, v213
	v_mul_f32_e32 v223, v36, v39
	v_lshlrev_b32_e32 v40, 16, v221
	v_mul_f32_e32 v224, v38, v40
	v_mul_f32_e32 v240, v35, v224
	v_exp_f32_e32 v34, v34
	v_rcp_f32_e32 v36, v34
	v_and_b32_e32 v37, 0xffff0000, v213
	v_mul_f32_e32 v34, v34, v37
	v_and_b32_e32 v38, 0xffff0000, v221
	v_cvt_pk_bf16_f32 v227, v223, v34
	ds_write_b64 v238, v[226:227] offset:48
	v_mul_f32_e32 v34, v36, v38
	v_cvt_pk_bf16_f32 v229, v224, v34
	v_mul_f32_e32 v34, v35, v34
	v_cvt_pk_bf16_f32 v243, v240, v34
	ds_write_b64 v238, v[228:229] offset:9264
	ds_write_b64 v238, v[242:243] offset:18480
	s_and_saveexec_b64 s[76:77], s[40:41]
	ds_write_b32 v134, v35
	s_or_b64 exec, exec, s[76:77]
	s_waitcnt lgkmcnt(0)
	s_barrier
	v_add_u32_e32 v172, v135, v117
	v_add_u32_e32 v173, v137, v154
	ds_read_b64_tr_b16 v[50:51], v166
	ds_read_b64_tr_b16 v[52:53], v166 offset:576
	s_mov_b64 s[76:77], -1
	s_and_b64 vcc, exec, s[78:79]
	s_cbranch_vccz .LBB0_418
	ds_read_b64_tr_b16 v[34:35], v173 offset:9216
	ds_read_b64_tr_b16 v[36:37], v173 offset:9792
	ds_read_b64_tr_b16 v[54:55], v157 offset:9216
	ds_read_b64_tr_b16 v[56:57], v157 offset:9792
	ds_read_b64_tr_b16 v[106:107], v166 offset:2304
	ds_read_b64_tr_b16 v[108:109], v166 offset:2880
	ds_read_b64_tr_b16 v[102:103], v166 offset:4608
	ds_read_b64_tr_b16 v[104:105], v166 offset:5184
	s_mov_b64 s[76:77], 0
	s_waitcnt lgkmcnt(6)
	v_mfma_f32_32x32x16_bf16 v[34:49], v[50:53], v[34:37], 0
	s_waitcnt lgkmcnt(2)
	v_mfma_f32_32x32x16_bf16 v[34:49], v[106:109], v[54:57], v[34:49]
	ds_read_b64_tr_b16 v[54:55], v158 offset:9216
	ds_read_b64_tr_b16 v[56:57], v158 offset:9792
	s_waitcnt lgkmcnt(0)
	v_mfma_f32_32x32x16_bf16 v[34:49], v[102:105], v[54:57], v[34:49]
	ds_read_b64_tr_b16 v[110:111], v166 offset:6912
	ds_read_b64_tr_b16 v[112:113], v166 offset:7488
	ds_read_b64_tr_b16 v[54:55], v159 offset:9216
	ds_read_b64_tr_b16 v[56:57], v159 offset:9792
	s_waitcnt lgkmcnt(0)
	v_mfma_f32_32x32x16_bf16 v[34:49], v[110:113], v[54:57], v[34:49]
.LBB0_418:
	s_andn2_b64 vcc, exec, s[76:77]
	s_cbranch_vccnz .LBB0_420
	ds_read_b64_tr_b16 v[106:107], v166 offset:2304
	ds_read_b64_tr_b16 v[108:109], v166 offset:2880
	ds_read_b64_tr_b16 v[102:103], v166 offset:4608
	ds_read_b64_tr_b16 v[104:105], v166 offset:5184
	ds_read_b64_tr_b16 v[110:111], v166 offset:6912
	ds_read_b64_tr_b16 v[112:113], v166 offset:7488
	s_nop 6
	v_mov_b32_e32 v34, 0
	v_mov_b32_e32 v35, 0
	v_mov_b32_e32 v36, 0
	v_mov_b32_e32 v37, 0
	v_mov_b32_e32 v38, 0
	v_mov_b32_e32 v39, 0
	v_mov_b32_e32 v40, 0
	v_mov_b32_e32 v41, 0
	v_mov_b32_e32 v42, 0
	v_mov_b32_e32 v43, 0
	v_mov_b32_e32 v44, 0
	v_mov_b32_e32 v45, 0
	v_mov_b32_e32 v46, 0
	v_mov_b32_e32 v47, 0
	v_mov_b32_e32 v48, 0
	v_mov_b32_e32 v49, 0
; __device__ __forceinline__ void gla_unit(LAS char* lds0, int b, int h, int dvh, bf16_t* Z, bf16_t* OT, const float* afw, const float* afb, const float* abw, const float* abb, bool dry) {
;     ...
; #pragma unroll
;             for (int k = 0; k < 4; ++k) {
;                 const bf16x8 a = *(const LAS bf16x8*)(lds + G_Q + (32 * I + r32) * GP + (16 * k + 8 * hi) * 2);
;                 const LAS char* sp = lds + G_SB + (16 * k + 8 * hi + q4) * GP + (32 * J + 16 * g16 + 4 * p4) * 2;
;                 const s16x4 l0 = trread(sp), l1 = trread(sp + 4 * GP);
;                 oacc = __builtin_amdgcn_mfma_f32_32x32x16_bf16(a, MK8(l0, l1), oacc, 0, 0, 0);
;             }
; #pragma unroll
;             for (int r = 0; r < 16; ++r) { const int i_ = 32 * I + crow(r, hi), j_ = 32 * J + r32;
;                 ((LAS bf16_t*)(lds + G_AM))[i_ * (GP / 2) + j_] = f2bf((i_ >= j_) ? Ac[r] : 0.f); }
;         }
;         asm volatile("s_waitcnt lgkmcnt(0)\n\ts_barrier" ::: "memory");
;         {
; #pragma unroll
;             for (int u = 0; u < 4; ++u) {
;                 const bf16x8 a = *(const LAS bf16x8*)(lds + G_AM + (32 * I + r32) * GP + (16 * u + 8 * hi) * 2);
;                 const LAS char* vp = lds + G_V + (16 * u + 8 * hi + q4) * GP + (32 * J + 16 * g16 + 4 * p4) * 2;
;                 const s16x4 l0 = trread(vp), l1 = trread(vp + 4 * GP);
;                 oacc = __builtin_amdgcn_mfma_f32_32x32x16_bf16(a, MK8(l0, l1), oacc, 0, 0, 0);
;             }
; #pragma unroll
;             for (int r = 0; r < 16; ++r) ((LAS bf16_t*)(lds + G_O))[(32 * I + crow(r, hi)) * (GP / 2) + 32 * J + r32] = f2bf(oacc[r]);
;             const int Dd = I;
; #pragma unroll
;             for (int k = 0; k < 4; ++k) { const f32x4 dc = *(const LAS f32x4*)(lds + G_DEC + (32 * Dd + 8 * k + 4 * hi) * 4);
; #pragma unroll
;                 for (int j = 0; j < 4; ++j) S[4 * k + j] *= dc[j]; }
; #pragma unroll
;             for (int u = 0; u < 4; ++u) {
;                 const LAS char* kp = lds + G_KD + (16 * u + 8 * hi + q4) * GP + (32 * Dd + 16 * g16 + 4 * p4) * 2;
;                 const LAS char* vp = lds + G_V + (16 * u + 8 * hi + q4) * GP + (32 * J + 16 * g16 + 4 * p4) * 2;
;                 const s16x4 k0 = trread(kp), k1 = trread(kp + 4 * GP), v0 = trread(vp), v1 = trread(vp + 4 * GP);
;                 S = __builtin_amdgcn_mfma_f32_32x32x16_bf16(MK8(k0, k1), MK8(v0, v1), S, 0, 0, 0);
.LBB0_420:
	s_nop 9
	ds_read_b128 v[54:57], v239 offset:46080
	ds_read_b128 v[174:177], v239 offset:46112
	ds_read_b128 v[178:181], v239 offset:46144
	ds_read_b128 v[188:191], v239 offset:46176
	v_cndmask_b32_e64 v34, v34, 0, s[42:43]
	v_cndmask_b32_e64 v35, v35, 0, s[44:45]
	v_cndmask_b32_e64 v36, v36, 0, s[46:47]
	v_cndmask_b32_e64 v37, v37, 0, s[50:51]
	v_cvt_pk_bf16_f32 v242, v34, v35
	v_cvt_pk_bf16_f32 v243, v36, v37
	ds_write_b64 v238, v[242:243] offset:36864
	s_waitcnt lgkmcnt(4)
	v_mfma_f32_32x32x16_bf16 v[50:65], v[50:53], v[54:57], 0
	v_cndmask_b32_e64 v38, v38, 0, s[52:53]
	v_cndmask_b32_e64 v39, v39, 0, s[54:55]
	v_cndmask_b32_e64 v40, v40, 0, s[56:57]
	v_cndmask_b32_e64 v41, v41, 0, s[58:59]
	v_cvt_pk_bf16_f32 v242, v38, v39
	v_cvt_pk_bf16_f32 v243, v40, v41
	ds_write_b64 v238, v[242:243] offset:36880
	s_waitcnt lgkmcnt(4)
	v_mfma_f32_32x32x16_bf16 v[50:65], v[106:109], v[174:177], v[50:65]
	v_cndmask_b32_e64 v42, v42, 0, s[60:61]
	v_cndmask_b32_e64 v43, v43, 0, s[62:63]
	v_cndmask_b32_e64 v44, v44, 0, s[64:65]
	v_cndmask_b32_e64 v45, v45, 0, s[66:67]
	v_cvt_pk_bf16_f32 v242, v42, v43
	v_cvt_pk_bf16_f32 v243, v44, v45
	ds_write_b64 v238, v[242:243] offset:36896
	s_waitcnt lgkmcnt(4)
	v_mfma_f32_32x32x16_bf16 v[50:65], v[102:105], v[178:181], v[50:65]
	v_cndmask_b32_e64 v46, v46, 0, s[68:69]
	v_cndmask_b32_e64 v47, v47, 0, s[70:71]
	v_cndmask_b32_e64 v48, v48, 0, s[72:73]
	v_cndmask_b32_e64 v49, v49, 0, s[74:75]
	v_cvt_pk_bf16_f32 v242, v46, v47
	v_cvt_pk_bf16_f32 v243, v48, v49
	ds_write_b64 v238, v[242:243] offset:36912
	s_waitcnt lgkmcnt(4)
	v_mfma_f32_32x32x16_bf16 v[50:65], v[110:113], v[188:191], v[50:65]
	s_waitcnt lgkmcnt(0)
	s_barrier
	ds_read_b64_tr_b16 v[34:35], v166 offset:36864
	ds_read_b64_tr_b16 v[36:37], v166 offset:37440
	ds_read_b64_tr_b16 v[38:39], v173 offset:27648
	ds_read_b64_tr_b16 v[40:41], v173 offset:28224
	ds_read_b64_tr_b16 v[42:43], v166 offset:39168
	ds_read_b64_tr_b16 v[44:45], v166 offset:39744
	ds_read_b64_tr_b16 v[46:47], v157 offset:27648
	ds_read_b64_tr_b16 v[48:49], v157 offset:28224
	s_andn2_b64 vcc, exec, s[2:3]
	s_mov_b64 s[2:3], -1
	s_waitcnt lgkmcnt(4)
	v_mfma_f32_32x32x16_bf16 v[50:65], v[34:37], v[38:41], v[50:65]
	ds_read_b64_tr_b16 v[34:35], v166 offset:41472
	ds_read_b64_tr_b16 v[36:37], v166 offset:42048
	ds_read_b64_tr_b16 v[38:39], v158 offset:27648
	ds_read_b64_tr_b16 v[40:41], v158 offset:28224
	s_waitcnt lgkmcnt(4)
	v_mfma_f32_32x32x16_bf16 v[50:65], v[42:45], v[46:49], v[50:65]
	ds_read_b64_tr_b16 v[42:43], v166 offset:43776
	ds_read_b64_tr_b16 v[44:45], v166 offset:44352
	ds_read_b64_tr_b16 v[46:47], v159 offset:27648
	ds_read_b64_tr_b16 v[48:49], v159 offset:28224
	s_waitcnt lgkmcnt(4)
	v_mfma_f32_32x32x16_bf16 v[50:65], v[34:37], v[38:41], v[50:65]
	s_waitcnt lgkmcnt(0)
	v_mfma_f32_32x32x16_bf16 v[50:65], v[42:45], v[46:49], v[50:65]
	s_nop 11
	v_cvt_pk_bf16_f32 v34, v50, s0
	ds_write_b16 v161, v34 offset:55296
	v_cvt_pk_bf16_f32 v34, v51, s0
	ds_write_b16 v161, v34 offset:55440
	v_cvt_pk_bf16_f32 v34, v52, s0
	ds_write_b16 v161, v34 offset:55584
	v_cvt_pk_bf16_f32 v34, v53, s0
	ds_write_b16 v161, v34 offset:55728
	v_cvt_pk_bf16_f32 v34, v54, s0
	ds_write_b16 v161, v34 offset:56448
	v_cvt_pk_bf16_f32 v34, v55, s0
	ds_write_b16 v161, v34 offset:56592
	v_cvt_pk_bf16_f32 v34, v56, s0
	ds_write_b16 v161, v34 offset:56736
	v_cvt_pk_bf16_f32 v34, v57, s0
	ds_write_b16 v161, v34 offset:56880
	v_cvt_pk_bf16_f32 v34, v58, s0
	ds_write_b16 v161, v34 offset:57600
	v_cvt_pk_bf16_f32 v34, v59, s0
	ds_write_b16 v161, v34 offset:57744
	v_cvt_pk_bf16_f32 v34, v60, s0
	ds_write_b16 v161, v34 offset:57888
	v_cvt_pk_bf16_f32 v34, v61, s0
	ds_write_b16 v161, v34 offset:58032
	v_cvt_pk_bf16_f32 v34, v62, s0
	ds_write_b16 v161, v34 offset:58752
	v_cvt_pk_bf16_f32 v34, v63, s0
	ds_write_b16 v161, v34 offset:58896
	v_cvt_pk_bf16_f32 v34, v64, s0
	ds_write_b16 v161, v34 offset:59040
	v_cvt_pk_bf16_f32 v34, v65, s0
	ds_write_b16 v161, v34 offset:59184
	ds_read_b128 v[34:37], v165
	ds_read_b128 v[38:41], v164
	ds_read_b128 v[42:45], v163
	ds_read_b128 v[46:49], v162
	s_waitcnt lgkmcnt(3)
	v_pk_mul_f32 v[30:31], v[30:31], v[34:35]
	s_waitcnt lgkmcnt(2)
	v_pk_mul_f32 v[26:27], v[26:27], v[38:39]
	s_waitcnt lgkmcnt(1)
	v_pk_mul_f32 v[22:23], v[22:23], v[42:43]
	s_waitcnt lgkmcnt(0)
	v_pk_mul_f32 v[18:19], v[18:19], v[46:47]
	v_pk_mul_f32 v[32:33], v[32:33], v[36:37]
	v_pk_mul_f32 v[28:29], v[28:29], v[40:41]
	v_pk_mul_f32 v[24:25], v[24:25], v[44:45]
	v_pk_mul_f32 v[20:21], v[20:21], v[48:49]
	ds_read_b128 v[34:37], v172 offset:18432
	ds_read_b64_tr_b16 v[38:39], v173 offset:27648
	ds_read_b64_tr_b16 v[40:41], v173 offset:28224
	ds_read_b128 v[42:45], v172 offset:18464
	ds_read_b64_tr_b16 v[46:47], v173 offset:29952
	ds_read_b64_tr_b16 v[48:49], v173 offset:30528
	ds_read_b64_tr_b16 v[50:51], v173 offset:32256
	ds_read_b64_tr_b16 v[56:57], v173 offset:35136
	s_waitcnt lgkmcnt(5)
	v_mfma_f32_32x32x16_bf16 v[18:33], v[34:37], v[38:41], v[18:33]
	ds_read_b128 v[34:37], v172 offset:18496
	ds_read_b64_tr_b16 v[52:53], v173 offset:32832
	ds_read_b64_tr_b16 v[54:55], v173 offset:34560
	ds_read_b128 v[38:41], v172 offset:18528
	s_waitcnt lgkmcnt(0)
	s_barrier
	s_waitcnt lgkmcnt(8)
	v_mfma_f32_32x32x16_bf16 v[18:33], v[42:45], v[46:49], v[18:33]
	s_waitcnt lgkmcnt(3)
	v_mfma_f32_32x32x16_bf16 v[18:33], v[34:37], v[50:53], v[18:33]
	s_waitcnt lgkmcnt(0)
	v_mfma_f32_32x32x16_bf16 v[18:33], v[38:41], v[54:57], v[18:33]
	s_nop 11
	v_cvt_pk_bf16_f32 v242, v18, v19
	v_cvt_pk_bf16_f32 v243, v20, v21
	ds_write_b64 v238, v[242:243] offset:46080
	v_cvt_pk_bf16_f32 v242, v22, v23
	v_cvt_pk_bf16_f32 v243, v24, v25
	ds_write_b64 v238, v[242:243] offset:46096
	v_cvt_pk_bf16_f32 v242, v26, v27
	v_cvt_pk_bf16_f32 v243, v28, v29
	ds_write_b64 v238, v[242:243] offset:46112
	v_cvt_pk_bf16_f32 v242, v30, v31
	v_cvt_pk_bf16_f32 v243, v32, v33
	ds_write_b64 v238, v[242:243] offset:46128
	ds_read_b128 v[38:41], v171 offset:55296
	ds_read_b128 v[34:37], v167 offset:55296
	s_cbranch_vccnz .LBB0_422
	s_mov_b64 s[2:3], 0
